# P0 x row loop: exact counted waits per row kind (first 7, middle 15, last 15-j) so ~7 row loads stay in flight per wave instead of ~3.5
# baseline (speedup 1.0000x reference)
; __device__ __forceinline__ unsigned pk2(float lo, float hi) { return f2bf(lo) | (f2bf(hi) << 16); }
; __device__ __forceinline__ float wave_sum(float v) {
; #pragma unroll
;     for (int o = 1; o < 64; o <<= 1) v += __shfl_xor(v, o);
;     return v;
; }
; __device__ __forceinline__ void p0_prologue(const Args& a, LAS unsigned char* lds) {
;     ...
;     { const float* x = a.in[0]; bf16* xb = (bf16*)(ws + WS_XB0); float* ss0 = (float*)(ws + WS_SS0);
;       for (int m = gw; m < M; m += NGW) { const f32x4* xr = (const f32x4*)(x + (size_t)m * D) + lane; u32x2* o8 = (u32x2*)(xb + (size_t)(m >> 8) * 8 * 65536 + (size_t)(m & 255) * 256) + lane; float s = 0.f;
; #pragma unroll
;           for (int j = 0; j < 8; ++j) { const f32x4 v = __builtin_nontemporal_load(xr + 64 * j); s += (v[0] * v[0] + v[1] * v[1]) + (v[2] * v[2] + v[3] * v[3]); u32x2 w; w.x = pk2(v[0], v[1]); w.y = pk2(v[2], v[3]); o8[(size_t)j * (65536 / 4)] = w; }
;           s = wave_sum(s); if (lane < 32) ss0[(size_t)m * 32 + lane] = lane == 0 ? s : 0.f; } }
.LBB0_319:
	v_readlane_b32 s0, v254, 9
	v_readlane_b32 s1, v254, 10
	s_or_b64 exec, exec, s[0:1]
	s_movk_i32 s0, 0x4000
	v_cmp_gt_i32_e32 vcc, s0, v150
	s_and_saveexec_b64 s[8:9], vcc
	v_readlane_b32 s92, v254, 5
	v_readlane_b32 s93, v254, 6
	s_cbranch_execz .LBB0_324
	v_mbcnt_lo_u32_b32 v2, -1, 0
	v_mbcnt_hi_u32_b32 v2, -1, v2
	v_and_b32_e32 v3, 64, v2
	v_add_u32_e32 v3, 64, v3
	v_xor_b32_e32 v4, 1, v2
	v_cmp_lt_i32_e32 vcc, v4, v3
	v_ashrrev_i32_e32 v151, 31, v150
	s_load_dwordx2 s[0:1], s[92:93], 0x0
	v_cndmask_b32_e32 v4, v2, v4, vcc
	s_waitcnt vmcnt(21)
	v_lshlrev_b32_e32 v16, 2, v4
	v_xor_b32_e32 v4, 2, v2
	v_cmp_lt_i32_e32 vcc, v4, v3
	v_mov_b32_e32 v7, 0
	v_readlane_b32 s6, v254, 7
	v_cndmask_b32_e32 v4, v2, v4, vcc
	v_lshlrev_b32_e32 v17, 2, v4
	v_xor_b32_e32 v4, 4, v2
	v_cmp_lt_i32_e32 vcc, v4, v3
	v_lshlrev_b32_e32 v6, 2, v152
	s_add_u32 s10, s74, 0x2000000
	v_cndmask_b32_e32 v4, v2, v4, vcc
	s_waitcnt vmcnt(20)
	v_lshlrev_b32_e32 v18, 2, v4
	v_xor_b32_e32 v4, 8, v2
	v_cmp_lt_i32_e32 vcc, v4, v3
	v_readlane_b32 s7, v254, 8
	s_addc_u32 s11, s75, 0
	v_cndmask_b32_e32 v4, v2, v4, vcc
	v_lshlrev_b32_e32 v19, 2, v4
	v_xor_b32_e32 v4, 16, v2
	v_cmp_lt_i32_e32 vcc, v4, v3
	s_lshl_b32 s3, s6, 11
	s_mov_b64 s[6:7], 0x200000
	v_cndmask_b32_e32 v4, v2, v4, vcc
	v_lshlrev_b32_e32 v20, 2, v4
	v_xor_b32_e32 v4, 32, v2
	v_cmp_lt_i32_e32 vcc, v4, v3
	v_lshlrev_b32_e32 v1, 8, v1
	s_ashr_i32 s43, s42, 31
	v_cndmask_b32_e32 v2, v2, v4, vcc
	v_lshlrev_b32_e32 v21, 2, v2
	v_lshlrev_b64 v[2:3], 7, v[150:151]
	v_lshl_add_u64 v[2:3], v[2:3], 0, v[6:7]
	v_lshl_add_u64 v[2:3], s[74:75], 0, v[2:3]
	v_lshl_add_u64 v[8:9], v[2:3], 0, s[6:7]
	v_lshlrev_b64 v[2:3], 13, v[150:151]
	v_lshl_or_b32 v2, v152, 4, v2
	s_waitcnt lgkmcnt(0)
	v_lshl_add_u64 v[2:3], s[0:1], 0, v[2:3]
	s_mov_b64 s[0:1], 0x1000
	v_cmp_gt_u32_e32 vcc, 32, v152
	v_cmp_eq_u32_e64 s[4:5], 0, v152
	v_lshl_add_u32 v1, s2, 11, v1
	s_lshl_b64 s[12:13], s[42:43], 7
	v_lshl_add_u64 v[10:11], v[2:3], 0, s[0:1]
	s_lshl_b64 s[14:15], s[42:43], 13
	s_mov_b64 s[16:17], 0
	v_lshlrev_b32_e32 v12, 3, v152
	v_mov_b32_e32 v13, v7
	s_movk_i32 s18, 0x7fff
	s_mov_b32 s19, 0x20000
	s_mov_b32 s20, 0x40000
	s_mov_b32 s21, 0x60000
	s_mov_b32 s22, 0x80000
	s_mov_b32 s23, 0xa0000
	s_mov_b32 s24, 0xc0000
	s_mov_b32 s25, 0xe0000
	s_movk_i32 s26, 0x3fff
	s_waitcnt vmcnt(19)
	v_mov_b32_e32 v22, 1
	s_load_dwordx2 s[0:1], s[92:93], 0x0
	v_readfirstlane_b32 s3, v150
	v_lshlrev_b32_e32 v10, 4, v152
	v_lshlrev_b32_e32 v11, 3, v152
	v_lshlrev_b32_e32 v12, 2, v152
	v_cmp_eq_u32_e64 s[4:5], 0, v152
	s_lshl_b32 s17, s42, 13
	s_lshl_b32 s6, s3, 13
	s_mov_b32 s19, 1
	s_waitcnt lgkmcnt(0)
	s_add_u32 s10, s0, s6
	s_addc_u32 s11, s1, 0
	s_add_u32 s10, s10, 0x1000
	s_addc_u32 s11, s11, 0
	global_load_dwordx4 v[24:27], v10, s[10:11] offset:-4096 nt
	global_load_dwordx4 v[28:31], v10, s[10:11] offset:-3072 nt
	global_load_dwordx4 v[32:35], v10, s[10:11] offset:-2048 nt
	global_load_dwordx4 v[36:39], v10, s[10:11] offset:-1024 nt
	global_load_dwordx4 v[40:43], v10, s[10:11] offset:0 nt
	global_load_dwordx4 v[44:47], v10, s[10:11] offset:1024 nt
	global_load_dwordx4 v[48:51], v10, s[10:11] offset:2048 nt
	global_load_dwordx4 v[52:55], v10, s[10:11] offset:3072 nt
.Lxcv_row:
	s_lshr_b32 s6, s3, 8
	s_lshl_b32 s6, s6, 20
	s_and_b32 s7, s3, 0xff
	s_lshl_b32 s7, s7, 9
	s_add_u32 s6, s6, s7
	s_add_u32 s6, s6, 0x2000000
	s_add_u32 s12, s74, s6
	s_addc_u32 s13, s75, 0
	s_add_u32 s16, s3, s42
	s_add_u32 s14, s10, s17
	s_addc_u32 s15, s11, 0
	s_mov_b64 s[22:23], exec
	s_cmp_lt_u32 s16, 0x4000
	s_cselect_b64 s[20:21], exec, 0
	s_cmp_eq_u32 s19, 1
	s_cbranch_scc1 .Lxcv_first
	s_cmp_lt_u32 s16, 0x4000
	s_cbranch_scc1 .Lxcv_mid
.Lxcv_last:
	s_waitcnt vmcnt(15)
	v_and_b32_sdwa v5, v27, v22 dst_sel:DWORD dst_unused:UNUSED_PAD src0_sel:WORD_1 src1_sel:DWORD
	v_and_b32_sdwa v7, v25, v22 dst_sel:DWORD dst_unused:UNUSED_PAD src0_sel:WORD_1 src1_sel:DWORD
	v_and_b32_sdwa v6, v26, v22 dst_sel:DWORD dst_unused:UNUSED_PAD src0_sel:WORD_1 src1_sel:DWORD
	v_and_b32_sdwa v23, v24, v22 dst_sel:DWORD dst_unused:UNUSED_PAD src0_sel:WORD_1 src1_sel:DWORD
	v_add3_u32 v5, v27, v5, s18
	v_add3_u32 v7, v25, v7, s18
	v_add3_u32 v23, v24, v23, s18
	v_add3_u32 v6, v26, v6, s18
	v_and_b32_e32 v5, 0xffff0000, v5
	v_and_b32_e32 v7, 0xffff0000, v7
	v_or_b32_sdwa v65, v5, v6 dst_sel:DWORD dst_unused:UNUSED_PAD src0_sel:DWORD src1_sel:WORD_1
	v_or_b32_sdwa v64, v7, v23 dst_sel:DWORD dst_unused:UNUSED_PAD src0_sel:DWORD src1_sel:WORD_1
	v_mul_f32_e32 v3, v25, v25
	v_mul_f32_e32 v4, v27, v27
	global_store_dwordx2 v11, v[64:65], s[12:13]
	v_fmac_f32_e32 v3, v24, v24
	v_fmac_f32_e32 v4, v26, v26
	v_add_f32_e32 v2, v3, v4
	s_mov_b64 exec, s[20:21]
	global_load_dwordx4 v[24:27], v10, s[14:15] offset:-4096 nt
	s_mov_b64 exec, s[22:23]
	s_waitcnt vmcnt(14)
	v_and_b32_sdwa v5, v31, v22 dst_sel:DWORD dst_unused:UNUSED_PAD src0_sel:WORD_1 src1_sel:DWORD
	v_and_b32_sdwa v7, v29, v22 dst_sel:DWORD dst_unused:UNUSED_PAD src0_sel:WORD_1 src1_sel:DWORD
	v_and_b32_sdwa v6, v30, v22 dst_sel:DWORD dst_unused:UNUSED_PAD src0_sel:WORD_1 src1_sel:DWORD
	v_and_b32_sdwa v23, v28, v22 dst_sel:DWORD dst_unused:UNUSED_PAD src0_sel:WORD_1 src1_sel:DWORD
	v_add3_u32 v5, v31, v5, s18
	v_add3_u32 v7, v29, v7, s18
	v_add3_u32 v23, v28, v23, s18
	v_add3_u32 v6, v30, v6, s18
	v_and_b32_e32 v5, 0xffff0000, v5
	v_and_b32_e32 v7, 0xffff0000, v7
	s_add_u32 s24, s12, 0x20000
	s_addc_u32 s25, s13, 0
	v_or_b32_sdwa v67, v5, v6 dst_sel:DWORD dst_unused:UNUSED_PAD src0_sel:DWORD src1_sel:WORD_1
	v_or_b32_sdwa v66, v7, v23 dst_sel:DWORD dst_unused:UNUSED_PAD src0_sel:DWORD src1_sel:WORD_1
	v_mul_f32_e32 v3, v29, v29
	v_mul_f32_e32 v4, v31, v31
	global_store_dwordx2 v11, v[66:67], s[24:25]
	v_fmac_f32_e32 v3, v28, v28
	v_fmac_f32_e32 v4, v30, v30
	v_add_f32_e32 v3, v3, v4
	v_add_f32_e32 v2, v2, v3
	s_mov_b64 exec, s[20:21]
	global_load_dwordx4 v[28:31], v10, s[14:15] offset:-3072 nt
	s_mov_b64 exec, s[22:23]
	s_waitcnt vmcnt(13)
; __device__ __forceinline__ unsigned pk2(float lo, float hi) { return f2bf(lo) | (f2bf(hi) << 16); }
; __device__ __forceinline__ void p0_prologue(const Args& a, LAS unsigned char* lds) {
;     ...
;       for (int m = gw; m < M; m += NGW) { const f32x4* xr = (const f32x4*)(x + (size_t)m * D) + lane; u32x2* o8 = (u32x2*)(xb + (size_t)(m >> 8) * 8 * 65536 + (size_t)(m & 255) * 256) + lane; float s = 0.f;
; #pragma unroll
;           for (int j = 0; j < 8; ++j) { const f32x4 v = __builtin_nontemporal_load(xr + 64 * j); s += (v[0] * v[0] + v[1] * v[1]) + (v[2] * v[2] + v[3] * v[3]); u32x2 w; w.x = pk2(v[0], v[1]); w.y = pk2(v[2], v[3]); o8[(size_t)j * (65536 / 4)] = w; }
	v_and_b32_sdwa v5, v35, v22 dst_sel:DWORD dst_unused:UNUSED_PAD src0_sel:WORD_1 src1_sel:DWORD
	v_and_b32_sdwa v7, v33, v22 dst_sel:DWORD dst_unused:UNUSED_PAD src0_sel:WORD_1 src1_sel:DWORD
	v_and_b32_sdwa v6, v34, v22 dst_sel:DWORD dst_unused:UNUSED_PAD src0_sel:WORD_1 src1_sel:DWORD
	v_and_b32_sdwa v23, v32, v22 dst_sel:DWORD dst_unused:UNUSED_PAD src0_sel:WORD_1 src1_sel:DWORD
	v_add3_u32 v5, v35, v5, s18
	v_add3_u32 v7, v33, v7, s18
	v_add3_u32 v23, v32, v23, s18
	v_add3_u32 v6, v34, v6, s18
	v_and_b32_e32 v5, 0xffff0000, v5
	v_and_b32_e32 v7, 0xffff0000, v7
	s_add_u32 s24, s12, 0x40000
	s_addc_u32 s25, s13, 0
	v_or_b32_sdwa v69, v5, v6 dst_sel:DWORD dst_unused:UNUSED_PAD src0_sel:DWORD src1_sel:WORD_1
	v_or_b32_sdwa v68, v7, v23 dst_sel:DWORD dst_unused:UNUSED_PAD src0_sel:DWORD src1_sel:WORD_1
	v_mul_f32_e32 v3, v33, v33
	v_mul_f32_e32 v4, v35, v35
	global_store_dwordx2 v11, v[68:69], s[24:25]
	v_fmac_f32_e32 v3, v32, v32
	v_fmac_f32_e32 v4, v34, v34
	v_add_f32_e32 v3, v3, v4
	v_add_f32_e32 v2, v2, v3
	s_mov_b64 exec, s[20:21]
	global_load_dwordx4 v[32:35], v10, s[14:15] offset:-2048 nt
	s_mov_b64 exec, s[22:23]
	s_waitcnt vmcnt(12)
	v_and_b32_sdwa v5, v39, v22 dst_sel:DWORD dst_unused:UNUSED_PAD src0_sel:WORD_1 src1_sel:DWORD
	v_and_b32_sdwa v7, v37, v22 dst_sel:DWORD dst_unused:UNUSED_PAD src0_sel:WORD_1 src1_sel:DWORD
	v_and_b32_sdwa v6, v38, v22 dst_sel:DWORD dst_unused:UNUSED_PAD src0_sel:WORD_1 src1_sel:DWORD
	v_and_b32_sdwa v23, v36, v22 dst_sel:DWORD dst_unused:UNUSED_PAD src0_sel:WORD_1 src1_sel:DWORD
	v_add3_u32 v5, v39, v5, s18
	v_add3_u32 v7, v37, v7, s18
	v_add3_u32 v23, v36, v23, s18
	v_add3_u32 v6, v38, v6, s18
	v_and_b32_e32 v5, 0xffff0000, v5
	v_and_b32_e32 v7, 0xffff0000, v7
	s_add_u32 s24, s12, 0x60000
	s_addc_u32 s25, s13, 0
	v_or_b32_sdwa v71, v5, v6 dst_sel:DWORD dst_unused:UNUSED_PAD src0_sel:DWORD src1_sel:WORD_1
	v_or_b32_sdwa v70, v7, v23 dst_sel:DWORD dst_unused:UNUSED_PAD src0_sel:DWORD src1_sel:WORD_1
	v_mul_f32_e32 v3, v37, v37
	v_mul_f32_e32 v4, v39, v39
	global_store_dwordx2 v11, v[70:71], s[24:25]
	v_fmac_f32_e32 v3, v36, v36
	v_fmac_f32_e32 v4, v38, v38
	v_add_f32_e32 v3, v3, v4
	v_add_f32_e32 v2, v2, v3
	s_mov_b64 exec, s[20:21]
	global_load_dwordx4 v[36:39], v10, s[14:15] offset:-1024 nt
	s_mov_b64 exec, s[22:23]
	s_waitcnt vmcnt(11)
	v_and_b32_sdwa v5, v43, v22 dst_sel:DWORD dst_unused:UNUSED_PAD src0_sel:WORD_1 src1_sel:DWORD
	v_and_b32_sdwa v7, v41, v22 dst_sel:DWORD dst_unused:UNUSED_PAD src0_sel:WORD_1 src1_sel:DWORD
	v_and_b32_sdwa v6, v42, v22 dst_sel:DWORD dst_unused:UNUSED_PAD src0_sel:WORD_1 src1_sel:DWORD
	v_and_b32_sdwa v23, v40, v22 dst_sel:DWORD dst_unused:UNUSED_PAD src0_sel:WORD_1 src1_sel:DWORD
	v_add3_u32 v5, v43, v5, s18
	v_add3_u32 v7, v41, v7, s18
	v_add3_u32 v23, v40, v23, s18
	v_add3_u32 v6, v42, v6, s18
	v_and_b32_e32 v5, 0xffff0000, v5
	v_and_b32_e32 v7, 0xffff0000, v7
	s_add_u32 s24, s12, 0x80000
	s_addc_u32 s25, s13, 0
	v_or_b32_sdwa v73, v5, v6 dst_sel:DWORD dst_unused:UNUSED_PAD src0_sel:DWORD src1_sel:WORD_1
	v_or_b32_sdwa v72, v7, v23 dst_sel:DWORD dst_unused:UNUSED_PAD src0_sel:DWORD src1_sel:WORD_1
	v_mul_f32_e32 v3, v41, v41
	v_mul_f32_e32 v4, v43, v43
	global_store_dwordx2 v11, v[72:73], s[24:25]
	v_fmac_f32_e32 v3, v40, v40
	v_fmac_f32_e32 v4, v42, v42
	v_add_f32_e32 v3, v3, v4
	v_add_f32_e32 v2, v2, v3
	s_mov_b64 exec, s[20:21]
	global_load_dwordx4 v[40:43], v10, s[14:15] offset:0 nt
	s_mov_b64 exec, s[22:23]
	s_waitcnt vmcnt(10)
	v_and_b32_sdwa v5, v47, v22 dst_sel:DWORD dst_unused:UNUSED_PAD src0_sel:WORD_1 src1_sel:DWORD
	v_and_b32_sdwa v7, v45, v22 dst_sel:DWORD dst_unused:UNUSED_PAD src0_sel:WORD_1 src1_sel:DWORD
	v_and_b32_sdwa v6, v46, v22 dst_sel:DWORD dst_unused:UNUSED_PAD src0_sel:WORD_1 src1_sel:DWORD
	v_and_b32_sdwa v23, v44, v22 dst_sel:DWORD dst_unused:UNUSED_PAD src0_sel:WORD_1 src1_sel:DWORD
	v_add3_u32 v5, v47, v5, s18
	v_add3_u32 v7, v45, v7, s18
	v_add3_u32 v23, v44, v23, s18
	v_add3_u32 v6, v46, v6, s18
	v_and_b32_e32 v5, 0xffff0000, v5
	v_and_b32_e32 v7, 0xffff0000, v7
	s_add_u32 s24, s12, 0xa0000
	s_addc_u32 s25, s13, 0
	v_or_b32_sdwa v75, v5, v6 dst_sel:DWORD dst_unused:UNUSED_PAD src0_sel:DWORD src1_sel:WORD_1
	v_or_b32_sdwa v74, v7, v23 dst_sel:DWORD dst_unused:UNUSED_PAD src0_sel:DWORD src1_sel:WORD_1
	v_mul_f32_e32 v3, v45, v45
	v_mul_f32_e32 v4, v47, v47
	global_store_dwordx2 v11, v[74:75], s[24:25]
	v_fmac_f32_e32 v3, v44, v44
	v_fmac_f32_e32 v4, v46, v46
	v_add_f32_e32 v3, v3, v4
	v_add_f32_e32 v2, v2, v3
	s_mov_b64 exec, s[20:21]
	global_load_dwordx4 v[44:47], v10, s[14:15] offset:1024 nt
	s_mov_b64 exec, s[22:23]
	s_waitcnt vmcnt(9)
	v_and_b32_sdwa v5, v51, v22 dst_sel:DWORD dst_unused:UNUSED_PAD src0_sel:WORD_1 src1_sel:DWORD
	v_and_b32_sdwa v7, v49, v22 dst_sel:DWORD dst_unused:UNUSED_PAD src0_sel:WORD_1 src1_sel:DWORD
	v_and_b32_sdwa v6, v50, v22 dst_sel:DWORD dst_unused:UNUSED_PAD src0_sel:WORD_1 src1_sel:DWORD
	v_and_b32_sdwa v23, v48, v22 dst_sel:DWORD dst_unused:UNUSED_PAD src0_sel:WORD_1 src1_sel:DWORD
	v_add3_u32 v5, v51, v5, s18
	v_add3_u32 v7, v49, v7, s18
	v_add3_u32 v23, v48, v23, s18
	v_add3_u32 v6, v50, v6, s18
	v_and_b32_e32 v5, 0xffff0000, v5
	v_and_b32_e32 v7, 0xffff0000, v7
	s_add_u32 s24, s12, 0xc0000
	s_addc_u32 s25, s13, 0
	v_or_b32_sdwa v77, v5, v6 dst_sel:DWORD dst_unused:UNUSED_PAD src0_sel:DWORD src1_sel:WORD_1
	v_or_b32_sdwa v76, v7, v23 dst_sel:DWORD dst_unused:UNUSED_PAD src0_sel:DWORD src1_sel:WORD_1
	v_mul_f32_e32 v3, v49, v49
	v_mul_f32_e32 v4, v51, v51
	global_store_dwordx2 v11, v[76:77], s[24:25]
	v_fmac_f32_e32 v3, v48, v48
	v_fmac_f32_e32 v4, v50, v50
	v_add_f32_e32 v3, v3, v4
	v_add_f32_e32 v2, v2, v3
	s_mov_b64 exec, s[20:21]
	global_load_dwordx4 v[48:51], v10, s[14:15] offset:2048 nt
	s_mov_b64 exec, s[22:23]
	s_waitcnt vmcnt(8)
	v_and_b32_sdwa v5, v55, v22 dst_sel:DWORD dst_unused:UNUSED_PAD src0_sel:WORD_1 src1_sel:DWORD
	v_and_b32_sdwa v7, v53, v22 dst_sel:DWORD dst_unused:UNUSED_PAD src0_sel:WORD_1 src1_sel:DWORD
	v_and_b32_sdwa v6, v54, v22 dst_sel:DWORD dst_unused:UNUSED_PAD src0_sel:WORD_1 src1_sel:DWORD
	v_and_b32_sdwa v23, v52, v22 dst_sel:DWORD dst_unused:UNUSED_PAD src0_sel:WORD_1 src1_sel:DWORD
	v_add3_u32 v5, v55, v5, s18
	v_add3_u32 v7, v53, v7, s18
	v_add3_u32 v23, v52, v23, s18
	v_add3_u32 v6, v54, v6, s18
	v_and_b32_e32 v5, 0xffff0000, v5
	v_and_b32_e32 v7, 0xffff0000, v7
	s_add_u32 s24, s12, 0xe0000
	s_addc_u32 s25, s13, 0
	v_or_b32_sdwa v79, v5, v6 dst_sel:DWORD dst_unused:UNUSED_PAD src0_sel:DWORD src1_sel:WORD_1
	v_or_b32_sdwa v78, v7, v23 dst_sel:DWORD dst_unused:UNUSED_PAD src0_sel:DWORD src1_sel:WORD_1
	v_mul_f32_e32 v3, v53, v53
	v_mul_f32_e32 v4, v55, v55
	global_store_dwordx2 v11, v[78:79], s[24:25]
	v_fmac_f32_e32 v3, v52, v52
	v_fmac_f32_e32 v4, v54, v54
	v_add_f32_e32 v3, v3, v4
	v_add_f32_e32 v2, v2, v3
	s_mov_b64 exec, s[20:21]
	global_load_dwordx4 v[52:55], v10, s[14:15] offset:3072 nt
	s_mov_b64 exec, s[22:23]
	s_branch .Lxcv_tail
; __device__ __forceinline__ unsigned pk2(float lo, float hi) { return f2bf(lo) | (f2bf(hi) << 16); }
; __device__ __forceinline__ void p0_prologue(const Args& a, LAS unsigned char* lds) {
;     ...
;       for (int m = gw; m < M; m += NGW) { const f32x4* xr = (const f32x4*)(x + (size_t)m * D) + lane; u32x2* o8 = (u32x2*)(xb + (size_t)(m >> 8) * 8 * 65536 + (size_t)(m & 255) * 256) + lane; float s = 0.f;
; #pragma unroll
;           for (int j = 0; j < 8; ++j) { const f32x4 v = __builtin_nontemporal_load(xr + 64 * j); s += (v[0] * v[0] + v[1] * v[1]) + (v[2] * v[2] + v[3] * v[3]); u32x2 w; w.x = pk2(v[0], v[1]); w.y = pk2(v[2], v[3]); o8[(size_t)j * (65536 / 4)] = w; }
.Lxcv_first:
	s_waitcnt vmcnt(7)
	v_and_b32_sdwa v5, v27, v22 dst_sel:DWORD dst_unused:UNUSED_PAD src0_sel:WORD_1 src1_sel:DWORD
	v_and_b32_sdwa v7, v25, v22 dst_sel:DWORD dst_unused:UNUSED_PAD src0_sel:WORD_1 src1_sel:DWORD
	v_and_b32_sdwa v6, v26, v22 dst_sel:DWORD dst_unused:UNUSED_PAD src0_sel:WORD_1 src1_sel:DWORD
	v_and_b32_sdwa v23, v24, v22 dst_sel:DWORD dst_unused:UNUSED_PAD src0_sel:WORD_1 src1_sel:DWORD
	v_add3_u32 v5, v27, v5, s18
	v_add3_u32 v7, v25, v7, s18
	v_add3_u32 v23, v24, v23, s18
	v_add3_u32 v6, v26, v6, s18
	v_and_b32_e32 v5, 0xffff0000, v5
	v_and_b32_e32 v7, 0xffff0000, v7
	v_or_b32_sdwa v65, v5, v6 dst_sel:DWORD dst_unused:UNUSED_PAD src0_sel:DWORD src1_sel:WORD_1
	v_or_b32_sdwa v64, v7, v23 dst_sel:DWORD dst_unused:UNUSED_PAD src0_sel:DWORD src1_sel:WORD_1
	v_mul_f32_e32 v3, v25, v25
	v_mul_f32_e32 v4, v27, v27
	global_store_dwordx2 v11, v[64:65], s[12:13]
	v_fmac_f32_e32 v3, v24, v24
	v_fmac_f32_e32 v4, v26, v26
	v_add_f32_e32 v2, v3, v4
	s_mov_b64 exec, s[20:21]
	global_load_dwordx4 v[24:27], v10, s[14:15] offset:-4096 nt
	s_mov_b64 exec, s[22:23]
	s_waitcnt vmcnt(7)
	v_and_b32_sdwa v5, v31, v22 dst_sel:DWORD dst_unused:UNUSED_PAD src0_sel:WORD_1 src1_sel:DWORD
	v_and_b32_sdwa v7, v29, v22 dst_sel:DWORD dst_unused:UNUSED_PAD src0_sel:WORD_1 src1_sel:DWORD
	v_and_b32_sdwa v6, v30, v22 dst_sel:DWORD dst_unused:UNUSED_PAD src0_sel:WORD_1 src1_sel:DWORD
	v_and_b32_sdwa v23, v28, v22 dst_sel:DWORD dst_unused:UNUSED_PAD src0_sel:WORD_1 src1_sel:DWORD
	v_add3_u32 v5, v31, v5, s18
	v_add3_u32 v7, v29, v7, s18
	v_add3_u32 v23, v28, v23, s18
	v_add3_u32 v6, v30, v6, s18
	v_and_b32_e32 v5, 0xffff0000, v5
	v_and_b32_e32 v7, 0xffff0000, v7
	s_add_u32 s24, s12, 0x20000
	s_addc_u32 s25, s13, 0
	v_or_b32_sdwa v67, v5, v6 dst_sel:DWORD dst_unused:UNUSED_PAD src0_sel:DWORD src1_sel:WORD_1
	v_or_b32_sdwa v66, v7, v23 dst_sel:DWORD dst_unused:UNUSED_PAD src0_sel:DWORD src1_sel:WORD_1
	v_mul_f32_e32 v3, v29, v29
	v_mul_f32_e32 v4, v31, v31
	global_store_dwordx2 v11, v[66:67], s[24:25]
	v_fmac_f32_e32 v3, v28, v28
	v_fmac_f32_e32 v4, v30, v30
	v_add_f32_e32 v3, v3, v4
	v_add_f32_e32 v2, v2, v3
	s_mov_b64 exec, s[20:21]
	global_load_dwordx4 v[28:31], v10, s[14:15] offset:-3072 nt
	s_mov_b64 exec, s[22:23]
	s_waitcnt vmcnt(7)
	v_and_b32_sdwa v5, v35, v22 dst_sel:DWORD dst_unused:UNUSED_PAD src0_sel:WORD_1 src1_sel:DWORD
	v_and_b32_sdwa v7, v33, v22 dst_sel:DWORD dst_unused:UNUSED_PAD src0_sel:WORD_1 src1_sel:DWORD
	v_and_b32_sdwa v6, v34, v22 dst_sel:DWORD dst_unused:UNUSED_PAD src0_sel:WORD_1 src1_sel:DWORD
	v_and_b32_sdwa v23, v32, v22 dst_sel:DWORD dst_unused:UNUSED_PAD src0_sel:WORD_1 src1_sel:DWORD
	v_add3_u32 v5, v35, v5, s18
	v_add3_u32 v7, v33, v7, s18
	v_add3_u32 v23, v32, v23, s18
	v_add3_u32 v6, v34, v6, s18
	v_and_b32_e32 v5, 0xffff0000, v5
	v_and_b32_e32 v7, 0xffff0000, v7
	s_add_u32 s24, s12, 0x40000
	s_addc_u32 s25, s13, 0
	v_or_b32_sdwa v69, v5, v6 dst_sel:DWORD dst_unused:UNUSED_PAD src0_sel:DWORD src1_sel:WORD_1
	v_or_b32_sdwa v68, v7, v23 dst_sel:DWORD dst_unused:UNUSED_PAD src0_sel:DWORD src1_sel:WORD_1
	v_mul_f32_e32 v3, v33, v33
	v_mul_f32_e32 v4, v35, v35
	global_store_dwordx2 v11, v[68:69], s[24:25]
	v_fmac_f32_e32 v3, v32, v32
	v_fmac_f32_e32 v4, v34, v34
	v_add_f32_e32 v3, v3, v4
	v_add_f32_e32 v2, v2, v3
	s_mov_b64 exec, s[20:21]
	global_load_dwordx4 v[32:35], v10, s[14:15] offset:-2048 nt
	s_mov_b64 exec, s[22:23]
	s_waitcnt vmcnt(7)
	v_and_b32_sdwa v5, v39, v22 dst_sel:DWORD dst_unused:UNUSED_PAD src0_sel:WORD_1 src1_sel:DWORD
	v_and_b32_sdwa v7, v37, v22 dst_sel:DWORD dst_unused:UNUSED_PAD src0_sel:WORD_1 src1_sel:DWORD
	v_and_b32_sdwa v6, v38, v22 dst_sel:DWORD dst_unused:UNUSED_PAD src0_sel:WORD_1 src1_sel:DWORD
	v_and_b32_sdwa v23, v36, v22 dst_sel:DWORD dst_unused:UNUSED_PAD src0_sel:WORD_1 src1_sel:DWORD
	v_add3_u32 v5, v39, v5, s18
	v_add3_u32 v7, v37, v7, s18
	v_add3_u32 v23, v36, v23, s18
	v_add3_u32 v6, v38, v6, s18
	v_and_b32_e32 v5, 0xffff0000, v5
	v_and_b32_e32 v7, 0xffff0000, v7
	s_add_u32 s24, s12, 0x60000
	s_addc_u32 s25, s13, 0
	v_or_b32_sdwa v71, v5, v6 dst_sel:DWORD dst_unused:UNUSED_PAD src0_sel:DWORD src1_sel:WORD_1
	v_or_b32_sdwa v70, v7, v23 dst_sel:DWORD dst_unused:UNUSED_PAD src0_sel:DWORD src1_sel:WORD_1
	v_mul_f32_e32 v3, v37, v37
	v_mul_f32_e32 v4, v39, v39
	global_store_dwordx2 v11, v[70:71], s[24:25]
	v_fmac_f32_e32 v3, v36, v36
	v_fmac_f32_e32 v4, v38, v38
	v_add_f32_e32 v3, v3, v4
	v_add_f32_e32 v2, v2, v3
	s_mov_b64 exec, s[20:21]
	global_load_dwordx4 v[36:39], v10, s[14:15] offset:-1024 nt
	s_mov_b64 exec, s[22:23]
	s_waitcnt vmcnt(7)
	v_and_b32_sdwa v5, v43, v22 dst_sel:DWORD dst_unused:UNUSED_PAD src0_sel:WORD_1 src1_sel:DWORD
	v_and_b32_sdwa v7, v41, v22 dst_sel:DWORD dst_unused:UNUSED_PAD src0_sel:WORD_1 src1_sel:DWORD
	v_and_b32_sdwa v6, v42, v22 dst_sel:DWORD dst_unused:UNUSED_PAD src0_sel:WORD_1 src1_sel:DWORD
	v_and_b32_sdwa v23, v40, v22 dst_sel:DWORD dst_unused:UNUSED_PAD src0_sel:WORD_1 src1_sel:DWORD
	v_add3_u32 v5, v43, v5, s18
	v_add3_u32 v7, v41, v7, s18
	v_add3_u32 v23, v40, v23, s18
	v_add3_u32 v6, v42, v6, s18
	v_and_b32_e32 v5, 0xffff0000, v5
	v_and_b32_e32 v7, 0xffff0000, v7
	s_add_u32 s24, s12, 0x80000
	s_addc_u32 s25, s13, 0
	v_or_b32_sdwa v73, v5, v6 dst_sel:DWORD dst_unused:UNUSED_PAD src0_sel:DWORD src1_sel:WORD_1
	v_or_b32_sdwa v72, v7, v23 dst_sel:DWORD dst_unused:UNUSED_PAD src0_sel:DWORD src1_sel:WORD_1
	v_mul_f32_e32 v3, v41, v41
	v_mul_f32_e32 v4, v43, v43
	global_store_dwordx2 v11, v[72:73], s[24:25]
	v_fmac_f32_e32 v3, v40, v40
	v_fmac_f32_e32 v4, v42, v42
	v_add_f32_e32 v3, v3, v4
	v_add_f32_e32 v2, v2, v3
	s_mov_b64 exec, s[20:21]
	global_load_dwordx4 v[40:43], v10, s[14:15] offset:0 nt
	s_mov_b64 exec, s[22:23]
	s_waitcnt vmcnt(7)
; __device__ __forceinline__ unsigned pk2(float lo, float hi) { return f2bf(lo) | (f2bf(hi) << 16); }
; __device__ __forceinline__ void p0_prologue(const Args& a, LAS unsigned char* lds) {
;     ...
;       for (int m = gw; m < M; m += NGW) { const f32x4* xr = (const f32x4*)(x + (size_t)m * D) + lane; u32x2* o8 = (u32x2*)(xb + (size_t)(m >> 8) * 8 * 65536 + (size_t)(m & 255) * 256) + lane; float s = 0.f;
; #pragma unroll
;           for (int j = 0; j < 8; ++j) { const f32x4 v = __builtin_nontemporal_load(xr + 64 * j); s += (v[0] * v[0] + v[1] * v[1]) + (v[2] * v[2] + v[3] * v[3]); u32x2 w; w.x = pk2(v[0], v[1]); w.y = pk2(v[2], v[3]); o8[(size_t)j * (65536 / 4)] = w; }
	v_and_b32_sdwa v5, v47, v22 dst_sel:DWORD dst_unused:UNUSED_PAD src0_sel:WORD_1 src1_sel:DWORD
	v_and_b32_sdwa v7, v45, v22 dst_sel:DWORD dst_unused:UNUSED_PAD src0_sel:WORD_1 src1_sel:DWORD
	v_and_b32_sdwa v6, v46, v22 dst_sel:DWORD dst_unused:UNUSED_PAD src0_sel:WORD_1 src1_sel:DWORD
	v_and_b32_sdwa v23, v44, v22 dst_sel:DWORD dst_unused:UNUSED_PAD src0_sel:WORD_1 src1_sel:DWORD
	v_add3_u32 v5, v47, v5, s18
	v_add3_u32 v7, v45, v7, s18
	v_add3_u32 v23, v44, v23, s18
	v_add3_u32 v6, v46, v6, s18
	v_and_b32_e32 v5, 0xffff0000, v5
	v_and_b32_e32 v7, 0xffff0000, v7
	s_add_u32 s24, s12, 0xa0000
	s_addc_u32 s25, s13, 0
	v_or_b32_sdwa v75, v5, v6 dst_sel:DWORD dst_unused:UNUSED_PAD src0_sel:DWORD src1_sel:WORD_1
	v_or_b32_sdwa v74, v7, v23 dst_sel:DWORD dst_unused:UNUSED_PAD src0_sel:DWORD src1_sel:WORD_1
	v_mul_f32_e32 v3, v45, v45
	v_mul_f32_e32 v4, v47, v47
	global_store_dwordx2 v11, v[74:75], s[24:25]
	v_fmac_f32_e32 v3, v44, v44
	v_fmac_f32_e32 v4, v46, v46
	v_add_f32_e32 v3, v3, v4
	v_add_f32_e32 v2, v2, v3
	s_mov_b64 exec, s[20:21]
	global_load_dwordx4 v[44:47], v10, s[14:15] offset:1024 nt
	s_mov_b64 exec, s[22:23]
	s_waitcnt vmcnt(7)
	v_and_b32_sdwa v5, v51, v22 dst_sel:DWORD dst_unused:UNUSED_PAD src0_sel:WORD_1 src1_sel:DWORD
	v_and_b32_sdwa v7, v49, v22 dst_sel:DWORD dst_unused:UNUSED_PAD src0_sel:WORD_1 src1_sel:DWORD
	v_and_b32_sdwa v6, v50, v22 dst_sel:DWORD dst_unused:UNUSED_PAD src0_sel:WORD_1 src1_sel:DWORD
	v_and_b32_sdwa v23, v48, v22 dst_sel:DWORD dst_unused:UNUSED_PAD src0_sel:WORD_1 src1_sel:DWORD
	v_add3_u32 v5, v51, v5, s18
	v_add3_u32 v7, v49, v7, s18
	v_add3_u32 v23, v48, v23, s18
	v_add3_u32 v6, v50, v6, s18
	v_and_b32_e32 v5, 0xffff0000, v5
	v_and_b32_e32 v7, 0xffff0000, v7
	s_add_u32 s24, s12, 0xc0000
	s_addc_u32 s25, s13, 0
	v_or_b32_sdwa v77, v5, v6 dst_sel:DWORD dst_unused:UNUSED_PAD src0_sel:DWORD src1_sel:WORD_1
	v_or_b32_sdwa v76, v7, v23 dst_sel:DWORD dst_unused:UNUSED_PAD src0_sel:DWORD src1_sel:WORD_1
	v_mul_f32_e32 v3, v49, v49
	v_mul_f32_e32 v4, v51, v51
	global_store_dwordx2 v11, v[76:77], s[24:25]
	v_fmac_f32_e32 v3, v48, v48
	v_fmac_f32_e32 v4, v50, v50
	v_add_f32_e32 v3, v3, v4
	v_add_f32_e32 v2, v2, v3
	s_mov_b64 exec, s[20:21]
	global_load_dwordx4 v[48:51], v10, s[14:15] offset:2048 nt
	s_mov_b64 exec, s[22:23]
	s_waitcnt vmcnt(7)
	v_and_b32_sdwa v5, v55, v22 dst_sel:DWORD dst_unused:UNUSED_PAD src0_sel:WORD_1 src1_sel:DWORD
	v_and_b32_sdwa v7, v53, v22 dst_sel:DWORD dst_unused:UNUSED_PAD src0_sel:WORD_1 src1_sel:DWORD
	v_and_b32_sdwa v6, v54, v22 dst_sel:DWORD dst_unused:UNUSED_PAD src0_sel:WORD_1 src1_sel:DWORD
	v_and_b32_sdwa v23, v52, v22 dst_sel:DWORD dst_unused:UNUSED_PAD src0_sel:WORD_1 src1_sel:DWORD
	v_add3_u32 v5, v55, v5, s18
	v_add3_u32 v7, v53, v7, s18
	v_add3_u32 v23, v52, v23, s18
	v_add3_u32 v6, v54, v6, s18
	v_and_b32_e32 v5, 0xffff0000, v5
	v_and_b32_e32 v7, 0xffff0000, v7
	s_add_u32 s24, s12, 0xe0000
	s_addc_u32 s25, s13, 0
	v_or_b32_sdwa v79, v5, v6 dst_sel:DWORD dst_unused:UNUSED_PAD src0_sel:DWORD src1_sel:WORD_1
	v_or_b32_sdwa v78, v7, v23 dst_sel:DWORD dst_unused:UNUSED_PAD src0_sel:DWORD src1_sel:WORD_1
	v_mul_f32_e32 v3, v53, v53
	v_mul_f32_e32 v4, v55, v55
	global_store_dwordx2 v11, v[78:79], s[24:25]
	v_fmac_f32_e32 v3, v52, v52
	v_fmac_f32_e32 v4, v54, v54
	v_add_f32_e32 v3, v3, v4
	v_add_f32_e32 v2, v2, v3
	s_mov_b64 exec, s[20:21]
	global_load_dwordx4 v[52:55], v10, s[14:15] offset:3072 nt
	s_mov_b64 exec, s[22:23]
	s_branch .Lxcv_tail
.Lxcv_mid:
	s_waitcnt vmcnt(15)
	v_and_b32_sdwa v5, v27, v22 dst_sel:DWORD dst_unused:UNUSED_PAD src0_sel:WORD_1 src1_sel:DWORD
	v_and_b32_sdwa v7, v25, v22 dst_sel:DWORD dst_unused:UNUSED_PAD src0_sel:WORD_1 src1_sel:DWORD
	v_and_b32_sdwa v6, v26, v22 dst_sel:DWORD dst_unused:UNUSED_PAD src0_sel:WORD_1 src1_sel:DWORD
	v_and_b32_sdwa v23, v24, v22 dst_sel:DWORD dst_unused:UNUSED_PAD src0_sel:WORD_1 src1_sel:DWORD
	v_add3_u32 v5, v27, v5, s18
	v_add3_u32 v7, v25, v7, s18
	v_add3_u32 v23, v24, v23, s18
	v_add3_u32 v6, v26, v6, s18
	v_and_b32_e32 v5, 0xffff0000, v5
	v_and_b32_e32 v7, 0xffff0000, v7
	v_or_b32_sdwa v65, v5, v6 dst_sel:DWORD dst_unused:UNUSED_PAD src0_sel:DWORD src1_sel:WORD_1
	v_or_b32_sdwa v64, v7, v23 dst_sel:DWORD dst_unused:UNUSED_PAD src0_sel:DWORD src1_sel:WORD_1
	v_mul_f32_e32 v3, v25, v25
	v_mul_f32_e32 v4, v27, v27
	global_store_dwordx2 v11, v[64:65], s[12:13]
	v_fmac_f32_e32 v3, v24, v24
	v_fmac_f32_e32 v4, v26, v26
	v_add_f32_e32 v2, v3, v4
	s_mov_b64 exec, s[20:21]
	global_load_dwordx4 v[24:27], v10, s[14:15] offset:-4096 nt
	s_mov_b64 exec, s[22:23]
	s_waitcnt vmcnt(15)
	v_and_b32_sdwa v5, v31, v22 dst_sel:DWORD dst_unused:UNUSED_PAD src0_sel:WORD_1 src1_sel:DWORD
	v_and_b32_sdwa v7, v29, v22 dst_sel:DWORD dst_unused:UNUSED_PAD src0_sel:WORD_1 src1_sel:DWORD
	v_and_b32_sdwa v6, v30, v22 dst_sel:DWORD dst_unused:UNUSED_PAD src0_sel:WORD_1 src1_sel:DWORD
	v_and_b32_sdwa v23, v28, v22 dst_sel:DWORD dst_unused:UNUSED_PAD src0_sel:WORD_1 src1_sel:DWORD
	v_add3_u32 v5, v31, v5, s18
	v_add3_u32 v7, v29, v7, s18
	v_add3_u32 v23, v28, v23, s18
	v_add3_u32 v6, v30, v6, s18
	v_and_b32_e32 v5, 0xffff0000, v5
	v_and_b32_e32 v7, 0xffff0000, v7
	s_add_u32 s24, s12, 0x20000
	s_addc_u32 s25, s13, 0
	v_or_b32_sdwa v67, v5, v6 dst_sel:DWORD dst_unused:UNUSED_PAD src0_sel:DWORD src1_sel:WORD_1
	v_or_b32_sdwa v66, v7, v23 dst_sel:DWORD dst_unused:UNUSED_PAD src0_sel:DWORD src1_sel:WORD_1
	v_mul_f32_e32 v3, v29, v29
	v_mul_f32_e32 v4, v31, v31
	global_store_dwordx2 v11, v[66:67], s[24:25]
	v_fmac_f32_e32 v3, v28, v28
	v_fmac_f32_e32 v4, v30, v30
	v_add_f32_e32 v3, v3, v4
	v_add_f32_e32 v2, v2, v3
	s_mov_b64 exec, s[20:21]
	global_load_dwordx4 v[28:31], v10, s[14:15] offset:-3072 nt
	s_mov_b64 exec, s[22:23]
	s_waitcnt vmcnt(15)
; __device__ __forceinline__ unsigned pk2(float lo, float hi) { return f2bf(lo) | (f2bf(hi) << 16); }
; __device__ __forceinline__ void p0_prologue(const Args& a, LAS unsigned char* lds) {
;     ...
;       for (int m = gw; m < M; m += NGW) { const f32x4* xr = (const f32x4*)(x + (size_t)m * D) + lane; u32x2* o8 = (u32x2*)(xb + (size_t)(m >> 8) * 8 * 65536 + (size_t)(m & 255) * 256) + lane; float s = 0.f;
; #pragma unroll
;           for (int j = 0; j < 8; ++j) { const f32x4 v = __builtin_nontemporal_load(xr + 64 * j); s += (v[0] * v[0] + v[1] * v[1]) + (v[2] * v[2] + v[3] * v[3]); u32x2 w; w.x = pk2(v[0], v[1]); w.y = pk2(v[2], v[3]); o8[(size_t)j * (65536 / 4)] = w; }
	v_and_b32_sdwa v5, v35, v22 dst_sel:DWORD dst_unused:UNUSED_PAD src0_sel:WORD_1 src1_sel:DWORD
	v_and_b32_sdwa v7, v33, v22 dst_sel:DWORD dst_unused:UNUSED_PAD src0_sel:WORD_1 src1_sel:DWORD
	v_and_b32_sdwa v6, v34, v22 dst_sel:DWORD dst_unused:UNUSED_PAD src0_sel:WORD_1 src1_sel:DWORD
	v_and_b32_sdwa v23, v32, v22 dst_sel:DWORD dst_unused:UNUSED_PAD src0_sel:WORD_1 src1_sel:DWORD
	v_add3_u32 v5, v35, v5, s18
	v_add3_u32 v7, v33, v7, s18
	v_add3_u32 v23, v32, v23, s18
	v_add3_u32 v6, v34, v6, s18
	v_and_b32_e32 v5, 0xffff0000, v5
	v_and_b32_e32 v7, 0xffff0000, v7
	s_add_u32 s24, s12, 0x40000
	s_addc_u32 s25, s13, 0
	v_or_b32_sdwa v69, v5, v6 dst_sel:DWORD dst_unused:UNUSED_PAD src0_sel:DWORD src1_sel:WORD_1
	v_or_b32_sdwa v68, v7, v23 dst_sel:DWORD dst_unused:UNUSED_PAD src0_sel:DWORD src1_sel:WORD_1
	v_mul_f32_e32 v3, v33, v33
	v_mul_f32_e32 v4, v35, v35
	global_store_dwordx2 v11, v[68:69], s[24:25]
	v_fmac_f32_e32 v3, v32, v32
	v_fmac_f32_e32 v4, v34, v34
	v_add_f32_e32 v3, v3, v4
	v_add_f32_e32 v2, v2, v3
	s_mov_b64 exec, s[20:21]
	global_load_dwordx4 v[32:35], v10, s[14:15] offset:-2048 nt
	s_mov_b64 exec, s[22:23]
	s_waitcnt vmcnt(15)
	v_and_b32_sdwa v5, v39, v22 dst_sel:DWORD dst_unused:UNUSED_PAD src0_sel:WORD_1 src1_sel:DWORD
	v_and_b32_sdwa v7, v37, v22 dst_sel:DWORD dst_unused:UNUSED_PAD src0_sel:WORD_1 src1_sel:DWORD
	v_and_b32_sdwa v6, v38, v22 dst_sel:DWORD dst_unused:UNUSED_PAD src0_sel:WORD_1 src1_sel:DWORD
	v_and_b32_sdwa v23, v36, v22 dst_sel:DWORD dst_unused:UNUSED_PAD src0_sel:WORD_1 src1_sel:DWORD
	v_add3_u32 v5, v39, v5, s18
	v_add3_u32 v7, v37, v7, s18
	v_add3_u32 v23, v36, v23, s18
	v_add3_u32 v6, v38, v6, s18
	v_and_b32_e32 v5, 0xffff0000, v5
	v_and_b32_e32 v7, 0xffff0000, v7
	s_add_u32 s24, s12, 0x60000
	s_addc_u32 s25, s13, 0
	v_or_b32_sdwa v71, v5, v6 dst_sel:DWORD dst_unused:UNUSED_PAD src0_sel:DWORD src1_sel:WORD_1
	v_or_b32_sdwa v70, v7, v23 dst_sel:DWORD dst_unused:UNUSED_PAD src0_sel:DWORD src1_sel:WORD_1
	v_mul_f32_e32 v3, v37, v37
	v_mul_f32_e32 v4, v39, v39
	global_store_dwordx2 v11, v[70:71], s[24:25]
	v_fmac_f32_e32 v3, v36, v36
	v_fmac_f32_e32 v4, v38, v38
	v_add_f32_e32 v3, v3, v4
	v_add_f32_e32 v2, v2, v3
	s_mov_b64 exec, s[20:21]
	global_load_dwordx4 v[36:39], v10, s[14:15] offset:-1024 nt
	s_mov_b64 exec, s[22:23]
	s_waitcnt vmcnt(15)
	v_and_b32_sdwa v5, v43, v22 dst_sel:DWORD dst_unused:UNUSED_PAD src0_sel:WORD_1 src1_sel:DWORD
	v_and_b32_sdwa v7, v41, v22 dst_sel:DWORD dst_unused:UNUSED_PAD src0_sel:WORD_1 src1_sel:DWORD
	v_and_b32_sdwa v6, v42, v22 dst_sel:DWORD dst_unused:UNUSED_PAD src0_sel:WORD_1 src1_sel:DWORD
	v_and_b32_sdwa v23, v40, v22 dst_sel:DWORD dst_unused:UNUSED_PAD src0_sel:WORD_1 src1_sel:DWORD
	v_add3_u32 v5, v43, v5, s18
	v_add3_u32 v7, v41, v7, s18
	v_add3_u32 v23, v40, v23, s18
	v_add3_u32 v6, v42, v6, s18
	v_and_b32_e32 v5, 0xffff0000, v5
	v_and_b32_e32 v7, 0xffff0000, v7
	s_add_u32 s24, s12, 0x80000
	s_addc_u32 s25, s13, 0
	v_or_b32_sdwa v73, v5, v6 dst_sel:DWORD dst_unused:UNUSED_PAD src0_sel:DWORD src1_sel:WORD_1
	v_or_b32_sdwa v72, v7, v23 dst_sel:DWORD dst_unused:UNUSED_PAD src0_sel:DWORD src1_sel:WORD_1
	v_mul_f32_e32 v3, v41, v41
	v_mul_f32_e32 v4, v43, v43
	global_store_dwordx2 v11, v[72:73], s[24:25]
	v_fmac_f32_e32 v3, v40, v40
	v_fmac_f32_e32 v4, v42, v42
	v_add_f32_e32 v3, v3, v4
	v_add_f32_e32 v2, v2, v3
	s_mov_b64 exec, s[20:21]
	global_load_dwordx4 v[40:43], v10, s[14:15] offset:0 nt
	s_mov_b64 exec, s[22:23]
	s_waitcnt vmcnt(15)
	v_and_b32_sdwa v5, v47, v22 dst_sel:DWORD dst_unused:UNUSED_PAD src0_sel:WORD_1 src1_sel:DWORD
	v_and_b32_sdwa v7, v45, v22 dst_sel:DWORD dst_unused:UNUSED_PAD src0_sel:WORD_1 src1_sel:DWORD
	v_and_b32_sdwa v6, v46, v22 dst_sel:DWORD dst_unused:UNUSED_PAD src0_sel:WORD_1 src1_sel:DWORD
	v_and_b32_sdwa v23, v44, v22 dst_sel:DWORD dst_unused:UNUSED_PAD src0_sel:WORD_1 src1_sel:DWORD
	v_add3_u32 v5, v47, v5, s18
	v_add3_u32 v7, v45, v7, s18
	v_add3_u32 v23, v44, v23, s18
	v_add3_u32 v6, v46, v6, s18
	v_and_b32_e32 v5, 0xffff0000, v5
	v_and_b32_e32 v7, 0xffff0000, v7
	s_add_u32 s24, s12, 0xa0000
	s_addc_u32 s25, s13, 0
	v_or_b32_sdwa v75, v5, v6 dst_sel:DWORD dst_unused:UNUSED_PAD src0_sel:DWORD src1_sel:WORD_1
	v_or_b32_sdwa v74, v7, v23 dst_sel:DWORD dst_unused:UNUSED_PAD src0_sel:DWORD src1_sel:WORD_1
	v_mul_f32_e32 v3, v45, v45
	v_mul_f32_e32 v4, v47, v47
	global_store_dwordx2 v11, v[74:75], s[24:25]
	v_fmac_f32_e32 v3, v44, v44
	v_fmac_f32_e32 v4, v46, v46
	v_add_f32_e32 v3, v3, v4
	v_add_f32_e32 v2, v2, v3
	s_mov_b64 exec, s[20:21]
	global_load_dwordx4 v[44:47], v10, s[14:15] offset:1024 nt
	s_mov_b64 exec, s[22:23]
	s_waitcnt vmcnt(15)
	v_and_b32_sdwa v5, v51, v22 dst_sel:DWORD dst_unused:UNUSED_PAD src0_sel:WORD_1 src1_sel:DWORD
	v_and_b32_sdwa v7, v49, v22 dst_sel:DWORD dst_unused:UNUSED_PAD src0_sel:WORD_1 src1_sel:DWORD
	v_and_b32_sdwa v6, v50, v22 dst_sel:DWORD dst_unused:UNUSED_PAD src0_sel:WORD_1 src1_sel:DWORD
	v_and_b32_sdwa v23, v48, v22 dst_sel:DWORD dst_unused:UNUSED_PAD src0_sel:WORD_1 src1_sel:DWORD
	v_add3_u32 v5, v51, v5, s18
	v_add3_u32 v7, v49, v7, s18
	v_add3_u32 v23, v48, v23, s18
	v_add3_u32 v6, v50, v6, s18
	v_and_b32_e32 v5, 0xffff0000, v5
	v_and_b32_e32 v7, 0xffff0000, v7
	s_add_u32 s24, s12, 0xc0000
	s_addc_u32 s25, s13, 0
	v_or_b32_sdwa v77, v5, v6 dst_sel:DWORD dst_unused:UNUSED_PAD src0_sel:DWORD src1_sel:WORD_1
	v_or_b32_sdwa v76, v7, v23 dst_sel:DWORD dst_unused:UNUSED_PAD src0_sel:DWORD src1_sel:WORD_1
	v_mul_f32_e32 v3, v49, v49
	v_mul_f32_e32 v4, v51, v51
	global_store_dwordx2 v11, v[76:77], s[24:25]
	v_fmac_f32_e32 v3, v48, v48
	v_fmac_f32_e32 v4, v50, v50
	v_add_f32_e32 v3, v3, v4
	v_add_f32_e32 v2, v2, v3
	s_mov_b64 exec, s[20:21]
	global_load_dwordx4 v[48:51], v10, s[14:15] offset:2048 nt
	s_mov_b64 exec, s[22:23]
	s_waitcnt vmcnt(15)
	v_and_b32_sdwa v5, v55, v22 dst_sel:DWORD dst_unused:UNUSED_PAD src0_sel:WORD_1 src1_sel:DWORD
	v_and_b32_sdwa v7, v53, v22 dst_sel:DWORD dst_unused:UNUSED_PAD src0_sel:WORD_1 src1_sel:DWORD
	v_and_b32_sdwa v6, v54, v22 dst_sel:DWORD dst_unused:UNUSED_PAD src0_sel:WORD_1 src1_sel:DWORD
	v_and_b32_sdwa v23, v52, v22 dst_sel:DWORD dst_unused:UNUSED_PAD src0_sel:WORD_1 src1_sel:DWORD
	v_add3_u32 v5, v55, v5, s18
	v_add3_u32 v7, v53, v7, s18
	v_add3_u32 v23, v52, v23, s18
	v_add3_u32 v6, v54, v6, s18
	v_and_b32_e32 v5, 0xffff0000, v5
	v_and_b32_e32 v7, 0xffff0000, v7
	s_add_u32 s24, s12, 0xe0000
	s_addc_u32 s25, s13, 0
	v_or_b32_sdwa v79, v5, v6 dst_sel:DWORD dst_unused:UNUSED_PAD src0_sel:DWORD src1_sel:WORD_1
	v_or_b32_sdwa v78, v7, v23 dst_sel:DWORD dst_unused:UNUSED_PAD src0_sel:DWORD src1_sel:WORD_1
	v_mul_f32_e32 v3, v53, v53
	v_mul_f32_e32 v4, v55, v55
	global_store_dwordx2 v11, v[78:79], s[24:25]
	v_fmac_f32_e32 v3, v52, v52
	v_fmac_f32_e32 v4, v54, v54
	v_add_f32_e32 v3, v3, v4
	v_add_f32_e32 v2, v2, v3
	s_mov_b64 exec, s[20:21]
	global_load_dwordx4 v[52:55], v10, s[14:15] offset:3072 nt
	s_mov_b64 exec, s[22:23]
; __device__ __forceinline__ float wave_sum(float v) {
; #pragma unroll
;     for (int o = 1; o < 64; o <<= 1) v += __shfl_xor(v, o);
;     return v;
; }
; __device__ __forceinline__ void p0_prologue(const Args& a, LAS unsigned char* lds) {
;     ...
;           s = wave_sum(s); if (lane < 32) ss0[(size_t)m * 32 + lane] = lane == 0 ? s : 0.f; } }
.Lxcv_tail:
	ds_bpermute_b32 v3, v16, v2
	s_lshl_b32 s6, s3, 7
	s_add_u32 s6, s6, 0x200000
	s_add_u32 s24, s74, s6
	s_addc_u32 s25, s75, 0
	s_waitcnt lgkmcnt(0)
	v_add_f32_e32 v2, v2, v3
	ds_bpermute_b32 v3, v17, v2
	s_waitcnt lgkmcnt(0)
	v_add_f32_e32 v2, v2, v3
	ds_bpermute_b32 v3, v18, v2
	s_waitcnt lgkmcnt(0)
	v_add_f32_e32 v2, v2, v3
	ds_bpermute_b32 v3, v19, v2
	s_waitcnt lgkmcnt(0)
	v_add_f32_e32 v2, v2, v3
	ds_bpermute_b32 v3, v20, v2
	s_waitcnt lgkmcnt(0)
	v_add_f32_e32 v2, v2, v3
	ds_bpermute_b32 v3, v21, v2
	s_waitcnt lgkmcnt(0)
	v_add_f32_e32 v2, v2, v3
	v_cmp_gt_u32_e32 vcc, 32, v152
	v_cndmask_b32_e64 v2, 0, v2, s[4:5]
	s_and_b64 exec, s[22:23], vcc
	global_store_dword v12, v2, s[24:25]
	s_mov_b64 exec, s[22:23]
	s_mov_b32 s19, 0
	s_mov_b32 s3, s16
	s_mov_b32 s10, s14
	s_mov_b32 s11, s15
	s_cmp_lt_u32 s3, 0x4000
	s_cbranch_scc1 .Lxcv_row
